# adaLN row reductions: xor 8/4/2/1 stages of the descending shfl_xor chain via DPP (row_ror, quad_perm) instead of ds_bpermute
# baseline (speedup 1.0000x reference)
.LBB0_405:
	s_or_b64 exec, exec, s[48:49]
	v_lshl_add_u64 v[2:3], v[2:3], 0, v[12:13]
	global_load_dwordx4 v[30:33], v[2:3], off
	global_load_dwordx4 v[34:37], v[2:3], off offset:1024
	global_load_dwordx4 v[38:41], v[2:3], off offset:2048
	s_nop 0
	global_load_dwordx4 v[2:5], v[2:3], off offset:3072
	s_nop 0
	global_load_dwordx4 v[42:45], v[8:9], off
	v_min_i32_e32 v0, 0x4000, v6
	v_ashrrev_i32_e32 v0, 11, v0
	v_mul_hi_i32_i24_e32 v21, 0x9000, v0
	v_mul_i32_i24_e32 v20, 0x9000, v0
	v_lshl_add_u64 v[20:21], s[14:15], 0, v[20:21]
	v_lshl_add_u64 v[22:23], v[20:21], 0, s[38:39]
	v_lshl_add_u64 v[46:47], v[22:23], 0, v[12:13]
	global_load_dwordx4 v[46:49], v[46:47], off
	v_lshl_add_u64 v[54:55], v[20:21], 0, v[12:13]
	global_load_dwordx4 v[50:53], v[54:55], off
	s_mov_b32 s4, s42
	s_waitcnt vmcnt(6)
	v_mov_b32_e32 v56, v31
	s_waitcnt vmcnt(5)
	v_mov_b32_e32 v57, v35
	v_mov_b32_e32 v20, v30
	v_mov_b32_e32 v21, v34
	s_waitcnt vmcnt(4)
	v_mov_b32_e32 v64, v39
	s_waitcnt vmcnt(3)
	v_mov_b32_e32 v65, v3
	v_pk_mul_f32 v[56:57], v[56:57], v[56:57]
	v_mov_b32_e32 v58, v32
	v_mov_b32_e32 v59, v36
	v_mov_b32_e32 v62, v38
	v_mov_b32_e32 v63, v2
	v_pk_mul_f32 v[64:65], v[64:65], v[64:65]
	v_pk_fma_f32 v[20:21], v[20:21], v[20:21], v[56:57]
	v_mov_b32_e32 v60, v33
	v_mov_b32_e32 v61, v37
	v_mov_b32_e32 v66, v40
	v_mov_b32_e32 v67, v4
	v_pk_fma_f32 v[56:57], v[62:63], v[62:63], v[64:65]
	v_pk_fma_f32 v[20:21], v[58:59], v[58:59], v[20:21]
	v_mov_b32_e32 v68, v41
	v_mov_b32_e32 v69, v5
	v_pk_fma_f32 v[56:57], v[66:67], v[66:67], v[56:57]
	v_pk_fma_f32 v[20:21], v[60:61], v[60:61], v[20:21]
	v_pk_fma_f32 v[56:57], v[68:69], v[68:69], v[56:57]
	v_add_f32_e32 v0, v20, v21
	v_add_f32_e32 v0, v0, v56
	v_add_f32_e32 v0, v0, v57
	ds_bpermute_b32 v20, v24, v0
	s_waitcnt vmcnt(2)
	v_mov_b32_e32 v57, v44
	v_mov_b32_e32 v44, v43
	v_mov_b32_e32 v43, v32
	s_waitcnt vmcnt(1)
	v_mov_b32_e32 v32, v46
	s_waitcnt lgkmcnt(0)
	v_add_f32_e32 v0, v0, v20
	ds_bpermute_b32 v20, v25, v0
	s_waitcnt vmcnt(0)
	v_mov_b32_e32 v59, v52
	v_mov_b32_e32 v52, v51
	v_mov_b32_e32 v58, v50
	v_mov_b32_e32 v50, v34
	s_waitcnt lgkmcnt(0)
	v_add_f32_e32 v0, v0, v20
	v_lshlrev_b64 v[20:21], 11, v[6:7]
	v_lshl_add_u64 v[20:21], v[10:11], 0, v[20:21]
	v_mov_b32_e32 v51, v36
	v_mov_b32_e32 v36, v35
	s_waitcnt lgkmcnt(0)
	s_nop 1
	v_add_f32_dpp v0, v0, v0 row_ror:8 row_mask:0xf bank_mask:0xf bound_ctrl:1
	v_mov_b32_e32 v56, v42
	v_mov_b32_e32 v42, v30
	v_mov_b32_e32 v30, v31
	v_mov_b32_e32 v31, v33
	s_waitcnt lgkmcnt(0)
	s_nop 1
	v_add_f32_dpp v0, v0, v0 row_ror:4 row_mask:0xf bank_mask:0xf bound_ctrl:1
	v_mov_b32_e32 v33, v48
	v_mov_b32_e32 v48, v47
	v_pk_add_f32 v[46:47], v[48:49], 1.0 op_sel_hi:[1,0]
	v_pk_add_f32 v[32:33], v[32:33], 1.0 op_sel_hi:[1,0]
	s_waitcnt lgkmcnt(0)
	s_nop 1
	v_add_f32_dpp v0, v0, v0 quad_perm:[2,3,0,1] row_mask:0xf bank_mask:0xf bound_ctrl:1
	s_waitcnt lgkmcnt(0)
	s_nop 1
	v_add_f32_dpp v0, v0, v0 quad_perm:[1,0,3,2] row_mask:0xf bank_mask:0xf bound_ctrl:1
	v_fmamk_f32 v0, v0, 0x3a800000, v174
	v_mul_f32_e32 v7, 0x4b800000, v0
	v_cmp_gt_f32_e32 vcc, s27, v0
	s_nop 1
	v_cndmask_b32_e32 v0, v0, v7, vcc
	v_rsq_f32_e32 v0, v0
	s_nop 0
	v_mul_f32_e32 v7, 0x45800000, v0
	v_cndmask_b32_e32 v0, v0, v7, vcc
	v_pk_mul_f32 v[30:31], v[30:31], v[0:1] op_sel_hi:[1,0]
	v_pk_mul_f32 v[42:43], v[42:43], v[0:1] op_sel_hi:[1,0]
	v_pk_mul_f32 v[30:31], v[44:45], v[30:31]
	v_pk_mul_f32 v[42:43], v[56:57], v[42:43]
	v_pk_fma_f32 v[30:31], v[46:47], v[30:31], v[52:53]
	v_pk_fma_f32 v[32:33], v[32:33], v[42:43], v[58:59]
	v_and_b32_sdwa v43, v31, v177 dst_sel:DWORD dst_unused:UNUSED_PAD src0_sel:WORD_1 src1_sel:DWORD
	v_and_b32_sdwa v44, v30, v177 dst_sel:DWORD dst_unused:UNUSED_PAD src0_sel:WORD_1 src1_sel:DWORD
	v_and_b32_sdwa v7, v33, v177 dst_sel:DWORD dst_unused:UNUSED_PAD src0_sel:WORD_1 src1_sel:DWORD
	v_and_b32_sdwa v42, v32, v177 dst_sel:DWORD dst_unused:UNUSED_PAD src0_sel:WORD_1 src1_sel:DWORD
	v_add3_u32 v31, v31, v43, s28
	v_add3_u32 v30, v30, v44, s28
	v_add3_u32 v32, v32, v42, s28
	v_add3_u32 v7, v33, v7, s28
	v_and_b32_e32 v31, 0xffff0000, v31
	v_and_b32_e32 v30, 0xffff0000, v30
	v_or_b32_sdwa v31, v31, v7 dst_sel:DWORD dst_unused:UNUSED_PAD src0_sel:DWORD src1_sel:WORD_1
	v_or_b32_sdwa v30, v30, v32 dst_sel:DWORD dst_unused:UNUSED_PAD src0_sel:DWORD src1_sel:WORD_1
	global_store_dwordx2 v[20:21], v[30:31], off
	global_load_dwordx4 v[30:33], v[8:9], off offset:1024
	v_lshl_add_u64 v[42:43], v[22:23], 0, v[14:15]
	global_load_dwordx4 v[42:45], v[42:43], off
	s_nop 0
	global_load_dwordx4 v[46:49], v[54:55], off offset:1024
	v_pk_mul_f32 v[34:35], v[50:51], v[0:1] op_sel_hi:[1,0]
	v_pk_mul_f32 v[36:37], v[36:37], v[0:1] op_sel_hi:[1,0]
	s_waitcnt vmcnt(2)
	v_mov_b32_e32 v50, v30
	v_mov_b32_e32 v51, v32
	s_waitcnt vmcnt(1)
	v_mov_b32_e32 v52, v42
	v_mov_b32_e32 v53, v44
	v_mov_b32_e32 v32, v31
	v_mov_b32_e32 v44, v43
	s_waitcnt vmcnt(0)
	v_mov_b32_e32 v56, v46
	v_mov_b32_e32 v57, v48
	v_mov_b32_e32 v48, v47
	v_pk_mul_f32 v[30:31], v[34:35], v[50:51]
	v_pk_add_f32 v[34:35], v[52:53], 1.0 op_sel_hi:[1,0]
	v_pk_mul_f32 v[32:33], v[36:37], v[32:33]
	v_pk_add_f32 v[36:37], v[44:45], 1.0 op_sel_hi:[1,0]
	v_pk_fma_f32 v[30:31], v[30:31], v[34:35], v[56:57]
	v_pk_fma_f32 v[32:33], v[32:33], v[36:37], v[48:49]
	v_and_b32_sdwa v7, v31, v177 dst_sel:DWORD dst_unused:UNUSED_PAD src0_sel:WORD_1 src1_sel:DWORD
	v_and_b32_sdwa v35, v33, v177 dst_sel:DWORD dst_unused:UNUSED_PAD src0_sel:WORD_1 src1_sel:DWORD
	v_and_b32_sdwa v36, v32, v177 dst_sel:DWORD dst_unused:UNUSED_PAD src0_sel:WORD_1 src1_sel:DWORD
	v_and_b32_sdwa v34, v30, v177 dst_sel:DWORD dst_unused:UNUSED_PAD src0_sel:WORD_1 src1_sel:DWORD
	v_add3_u32 v7, v31, v7, s28
	v_add3_u32 v31, v33, v35, s28
	v_add3_u32 v32, v32, v36, s28
	v_add3_u32 v30, v30, v34, s28
	v_and_b32_e32 v31, 0xffff0000, v31
	v_and_b32_e32 v32, 0xffff0000, v32
	v_or_b32_sdwa v31, v31, v7 dst_sel:DWORD dst_unused:UNUSED_PAD src0_sel:DWORD src1_sel:WORD_1
	v_or_b32_sdwa v30, v32, v30 dst_sel:DWORD dst_unused:UNUSED_PAD src0_sel:DWORD src1_sel:WORD_1
	global_store_dwordx2 v[20:21], v[30:31], off offset:512
	global_load_dwordx4 v[30:33], v[8:9], off offset:2048
	v_lshl_add_u64 v[34:35], v[22:23], 0, v[16:17]
	global_load_dwordx4 v[34:37], v[34:35], off
	s_nop 0
	global_load_dwordx4 v[42:45], v[54:55], off offset:2048
	v_mov_b32_e32 v46, v38
	v_mov_b32_e32 v47, v40
	v_mov_b32_e32 v38, v39
	v_mov_b32_e32 v39, v41
	v_pk_mul_f32 v[40:41], v[46:47], v[0:1] op_sel_hi:[1,0]
	v_pk_mul_f32 v[38:39], v[38:39], v[0:1] op_sel_hi:[1,0]
	v_lshl_add_u64 v[22:23], v[22:23], 0, v[18:19]
	s_waitcnt vmcnt(2)
	v_mov_b32_e32 v46, v30
	v_mov_b32_e32 v47, v32
	s_waitcnt vmcnt(1)
	v_mov_b32_e32 v48, v34
	v_mov_b32_e32 v49, v36
	v_mov_b32_e32 v32, v31
	v_mov_b32_e32 v36, v35
	s_waitcnt vmcnt(0)
	v_mov_b32_e32 v50, v42
	v_mov_b32_e32 v51, v44
	v_mov_b32_e32 v44, v43
	v_pk_mul_f32 v[30:31], v[40:41], v[46:47]
	v_pk_add_f32 v[34:35], v[48:49], 1.0 op_sel_hi:[1,0]
	v_pk_mul_f32 v[32:33], v[38:39], v[32:33]
	v_pk_add_f32 v[36:37], v[36:37], 1.0 op_sel_hi:[1,0]
	v_pk_fma_f32 v[30:31], v[30:31], v[34:35], v[50:51]
	v_pk_fma_f32 v[32:33], v[32:33], v[36:37], v[44:45]
	v_and_b32_sdwa v7, v31, v177 dst_sel:DWORD dst_unused:UNUSED_PAD src0_sel:WORD_1 src1_sel:DWORD
	v_and_b32_sdwa v35, v33, v177 dst_sel:DWORD dst_unused:UNUSED_PAD src0_sel:WORD_1 src1_sel:DWORD
	v_and_b32_sdwa v36, v32, v177 dst_sel:DWORD dst_unused:UNUSED_PAD src0_sel:WORD_1 src1_sel:DWORD
	v_and_b32_sdwa v34, v30, v177 dst_sel:DWORD dst_unused:UNUSED_PAD src0_sel:WORD_1 src1_sel:DWORD
	v_add3_u32 v7, v31, v7, s28
	v_add3_u32 v31, v33, v35, s28
	v_add3_u32 v32, v32, v36, s28
	v_add3_u32 v30, v30, v34, s28
	v_and_b32_e32 v31, 0xffff0000, v31
	v_and_b32_e32 v32, 0xffff0000, v32
	v_or_b32_sdwa v31, v31, v7 dst_sel:DWORD dst_unused:UNUSED_PAD src0_sel:DWORD src1_sel:WORD_1
	v_or_b32_sdwa v30, v32, v30 dst_sel:DWORD dst_unused:UNUSED_PAD src0_sel:DWORD src1_sel:WORD_1
	global_store_dwordx2 v[20:21], v[30:31], off offset:1024
	global_load_dwordx4 v[30:33], v[8:9], off offset:3072
	s_nop 0
	global_load_dwordx4 v[34:37], v[22:23], off
	global_load_dwordx4 v[38:41], v[54:55], off offset:3072
	v_mov_b32_e32 v22, v2
	v_mov_b32_e32 v23, v4
	v_mov_b32_e32 v4, v3
	v_pk_mul_f32 v[2:3], v[22:23], v[0:1] op_sel_hi:[1,0]
	v_pk_mul_f32 v[4:5], v[4:5], v[0:1] op_sel_hi:[1,0]
	s_waitcnt vmcnt(1)
	v_mov_b32_e32 v42, v34
	v_mov_b32_e32 v22, v30
	v_mov_b32_e32 v23, v32
	v_mov_b32_e32 v43, v36
	v_mov_b32_e32 v32, v31
	v_mov_b32_e32 v36, v35
	s_waitcnt vmcnt(0)
	v_mov_b32_e32 v44, v38
	v_mov_b32_e32 v45, v40
	v_mov_b32_e32 v40, v39
	v_pk_mul_f32 v[2:3], v[2:3], v[22:23]
	v_pk_add_f32 v[22:23], v[42:43], 1.0 op_sel_hi:[1,0]
	v_pk_mul_f32 v[4:5], v[4:5], v[32:33]
	v_pk_add_f32 v[30:31], v[36:37], 1.0 op_sel_hi:[1,0]
	v_pk_fma_f32 v[2:3], v[2:3], v[22:23], v[44:45]
	v_pk_fma_f32 v[4:5], v[4:5], v[30:31], v[40:41]
	v_and_b32_sdwa v0, v3, v177 dst_sel:DWORD dst_unused:UNUSED_PAD src0_sel:WORD_1 src1_sel:DWORD
	v_and_b32_sdwa v22, v5, v177 dst_sel:DWORD dst_unused:UNUSED_PAD src0_sel:WORD_1 src1_sel:DWORD
	v_and_b32_sdwa v23, v4, v177 dst_sel:DWORD dst_unused:UNUSED_PAD src0_sel:WORD_1 src1_sel:DWORD
	v_and_b32_sdwa v7, v2, v177 dst_sel:DWORD dst_unused:UNUSED_PAD src0_sel:WORD_1 src1_sel:DWORD
	v_add3_u32 v0, v3, v0, s28
	v_add3_u32 v3, v5, v22, s28
	v_add3_u32 v4, v4, v23, s28
	v_add3_u32 v2, v2, v7, s28
	v_and_b32_e32 v3, 0xffff0000, v3
	v_and_b32_e32 v4, 0xffff0000, v4
	v_or_b32_sdwa v3, v3, v0 dst_sel:DWORD dst_unused:UNUSED_PAD src0_sel:DWORD src1_sel:WORD_1
	v_or_b32_sdwa v2, v4, v2 dst_sel:DWORD dst_unused:UNUSED_PAD src0_sel:DWORD src1_sel:WORD_1
	global_store_dwordx2 v[20:21], v[2:3], off offset:1536
	s_nop 0
	v_lshl_add_u32 v6, s4, 3, v6
	v_cmp_lt_i32_e32 vcc, s29, v6
	s_or_b64 s[46:47], vcc, s[46:47]
	s_andn2_b64 exec, exec, s[46:47]
	s_cbranch_execz .LBB0_410

.LBB0_410:
	s_or_b64 exec, exec, s[44:45]
	s_waitcnt vmcnt(0)
	v_readlane_b32 s2, v253, 0
	v_readlane_b32 s3, v253, 1
	s_waitcnt lgkmcnt(0)
	s_barrier
	s_and_saveexec_b64 s[6:7], s[2:3]
	s_xor_b64 s[14:15], exec, s[6:7]
	s_cbranch_execz .LBB0_463
	s_waitcnt vmcnt(0) expcnt(0) lgkmcnt(0)
	ds_read_b32 v3, v175
	ds_read_b32 v2, v176
	s_waitcnt lgkmcnt(0)
	v_cmp_ne_u32_e32 vcc, 0, v3
	s_cbranch_vccnz .LBB0_426
	s_mov_b32 s4, 1
	s_branch .LBB0_414

.LBB0_604:
	s_or_b64 exec, exec, s[46:47]
	v_lshl_add_u64 v[2:3], v[2:3], 0, v[0:1]
	global_load_dwordx4 v[36:39], v[2:3], off
	global_load_dwordx4 v[40:43], v[2:3], off offset:1024
	global_load_dwordx4 v[44:47], v[2:3], off offset:2048
	s_nop 0
	global_load_dwordx4 v[2:5], v[2:3], off offset:3072
	s_nop 0
	global_load_dwordx4 v[48:51], v[8:9], off
	global_load_dwordx4 v[78:81], v[10:11], off
	global_load_dwordx4 v[90:93], v[12:13], off
	global_load_dwordx4 v[102:105], v[14:15], off
	v_min_i32_e32 v19, 0x4000, v6
	v_ashrrev_i32_e32 v19, 11, v19
	v_mul_hi_i32_i24_e32 v25, 0x9000, v19
	v_mul_i32_i24_e32 v24, 0x9000, v19
	v_lshl_add_u64 v[24:25], s[16:17], 0, v[24:25]
	v_lshl_add_u64 v[26:27], v[24:25], 0, s[38:39]
	v_lshl_add_u64 v[28:29], v[26:27], 0, v[0:1]
	global_load_dwordx4 v[52:55], v[28:29], off
	global_load_dwordx4 v[82:85], v[28:29], off offset:1024
	global_load_dwordx4 v[94:97], v[28:29], off offset:2048
	global_load_dwordx4 v[106:109], v[28:29], off offset:3072
	v_lshl_add_u64 v[28:29], v[24:25], 0, v[0:1]
	global_load_dwordx4 v[56:59], v[28:29], off
	global_load_dwordx4 v[86:89], v[28:29], off offset:1024
	global_load_dwordx4 v[98:101], v[28:29], off offset:2048
	global_load_dwordx4 v[110:113], v[28:29], off offset:3072
	s_mov_b32 s4, s42
	s_waitcnt vmcnt(15)
	v_mov_b32_e32 v60, v37
	s_waitcnt vmcnt(14)
	v_mov_b32_e32 v61, v41
	v_mov_b32_e32 v24, v36
	v_mov_b32_e32 v25, v40
	s_waitcnt vmcnt(13)
	v_mov_b32_e32 v68, v45
	s_waitcnt vmcnt(12)
	v_mov_b32_e32 v69, v3
	v_pk_mul_f32 v[60:61], v[60:61], v[60:61]
	v_mov_b32_e32 v62, v38
	v_mov_b32_e32 v63, v42
	v_mov_b32_e32 v66, v44
	v_mov_b32_e32 v67, v2
	v_pk_mul_f32 v[68:69], v[68:69], v[68:69]
	v_pk_fma_f32 v[24:25], v[24:25], v[24:25], v[60:61]
	v_mov_b32_e32 v64, v39
	v_mov_b32_e32 v65, v43
	v_mov_b32_e32 v70, v46
	v_mov_b32_e32 v71, v4
	v_pk_fma_f32 v[60:61], v[66:67], v[66:67], v[68:69]
	v_pk_fma_f32 v[24:25], v[62:63], v[62:63], v[24:25]
	v_mov_b32_e32 v72, v47
	v_mov_b32_e32 v73, v5
	v_pk_fma_f32 v[60:61], v[70:71], v[70:71], v[60:61]
	v_pk_fma_f32 v[24:25], v[64:65], v[64:65], v[24:25]
	v_pk_fma_f32 v[60:61], v[72:73], v[72:73], v[60:61]
	v_add_f32_e32 v19, v24, v25
	v_add_f32_e32 v19, v19, v60
	v_add_f32_e32 v19, v19, v61
	ds_bpermute_b32 v21, v30, v19
	v_lshlrev_b64 v[24:25], 11, v[6:7]
	s_waitcnt vmcnt(11)
	v_mov_b32_e32 v60, v48
	v_mov_b32_e32 v48, v36
	v_mov_b32_e32 v36, v37
	s_waitcnt lgkmcnt(0)
	v_add_f32_e32 v19, v19, v21
	ds_bpermute_b32 v21, v31, v19
	v_mov_b32_e32 v37, v39
	s_waitcnt vmcnt(3)
	v_mov_b32_e32 v62, v56
	v_mov_b32_e32 v61, v50
	v_mov_b32_e32 v50, v49
	s_waitcnt lgkmcnt(0)
	v_add_f32_e32 v21, v19, v21
	v_mov_b32_e32 v49, v38
	v_mov_b32_e32 v39, v54
	v_mov_b32_e32 v54, v53
	v_mov_b32_e32 v38, v52
	s_waitcnt lgkmcnt(0)
	s_nop 1
	v_add_f32_dpp v7, v21, v21 row_ror:8 row_mask:0xf bank_mask:0xf bound_ctrl:1
	v_mov_b32_e32 v63, v58
	v_mov_b32_e32 v58, v57
	v_pk_add_f32 v[52:53], v[54:55], 1.0 op_sel_hi:[1,0]
	v_pk_add_f32 v[38:39], v[38:39], 1.0 op_sel_hi:[1,0]
	s_waitcnt lgkmcnt(0)
	s_nop 1
	v_add_f32_dpp v7, v7, v7 row_ror:4 row_mask:0xf bank_mask:0xf bound_ctrl:1
	v_lshl_add_u64 v[24:25], v[16:17], 0, v[24:25]
	v_mov_b32_e32 v19, v1
	s_waitcnt lgkmcnt(0)
	s_nop 1
	v_add_f32_dpp v7, v7, v7 quad_perm:[2,3,0,1] row_mask:0xf bank_mask:0xf bound_ctrl:1
	s_waitcnt lgkmcnt(0)
	s_nop 1
	v_add_f32_dpp v7, v7, v7 quad_perm:[1,0,3,2] row_mask:0xf bank_mask:0xf bound_ctrl:1
	v_fmamk_f32 v7, v7, 0x3a800000, v174
	v_mul_f32_e32 v21, 0x4b800000, v7
	v_cmp_gt_f32_e32 vcc, s27, v7
	s_nop 1
	v_cndmask_b32_e32 v7, v7, v21, vcc
	v_rsq_f32_e32 v7, v7
	s_nop 0
	v_mul_f32_e32 v21, 0x45800000, v7
	v_cndmask_b32_e32 v56, v7, v21, vcc
	v_pk_mul_f32 v[36:37], v[36:37], v[56:57] op_sel_hi:[1,0]
	v_pk_mul_f32 v[48:49], v[48:49], v[56:57] op_sel_hi:[1,0]
	v_pk_mul_f32 v[36:37], v[50:51], v[36:37]
	v_pk_mul_f32 v[48:49], v[60:61], v[48:49]
	v_pk_fma_f32 v[36:37], v[52:53], v[36:37], v[58:59]
	v_pk_fma_f32 v[38:39], v[38:39], v[48:49], v[62:63]
	v_and_b32_sdwa v23, v37, v177 dst_sel:DWORD dst_unused:UNUSED_PAD src0_sel:WORD_1 src1_sel:DWORD
	v_and_b32_sdwa v48, v36, v177 dst_sel:DWORD dst_unused:UNUSED_PAD src0_sel:WORD_1 src1_sel:DWORD
	v_and_b32_sdwa v7, v39, v177 dst_sel:DWORD dst_unused:UNUSED_PAD src0_sel:WORD_1 src1_sel:DWORD
	v_and_b32_sdwa v21, v38, v177 dst_sel:DWORD dst_unused:UNUSED_PAD src0_sel:WORD_1 src1_sel:DWORD
	v_add3_u32 v23, v37, v23, s28
	v_add3_u32 v36, v36, v48, s28
	v_add3_u32 v21, v38, v21, s28
	v_add3_u32 v7, v39, v7, s28
	v_and_b32_e32 v23, 0xffff0000, v23
	v_and_b32_e32 v36, 0xffff0000, v36
	v_or_b32_sdwa v37, v23, v7 dst_sel:DWORD dst_unused:UNUSED_PAD src0_sel:DWORD src1_sel:WORD_1
	v_or_b32_sdwa v36, v36, v21 dst_sel:DWORD dst_unused:UNUSED_PAD src0_sel:DWORD src1_sel:WORD_1
	global_store_dwordx2 v[24:25], v[36:37], off
	v_lshl_add_u64 v[48:49], v[26:27], 0, v[18:19]
	s_waitcnt vmcnt(1)
	v_mov_b32_e32 v52, v86
	v_mov_b32_e32 v53, v87
	v_mov_b32_e32 v54, v88
	v_mov_b32_e32 v55, v89
	v_mov_b32_e32 v48, v82
	v_mov_b32_e32 v49, v83
	v_mov_b32_e32 v50, v84
	v_mov_b32_e32 v51, v85
	v_mov_b32_e32 v36, v78
	v_mov_b32_e32 v37, v79
	v_mov_b32_e32 v38, v80
	v_mov_b32_e32 v39, v81
	v_mov_b32_e32 v58, v40
	v_mov_b32_e32 v59, v42
	v_mov_b32_e32 v42, v41
	v_pk_mul_f32 v[40:41], v[58:59], v[56:57] op_sel_hi:[1,0]
	v_pk_mul_f32 v[42:43], v[42:43], v[56:57] op_sel_hi:[1,0]
	v_mov_b32_e32 v21, v1
	v_mov_b32_e32 v58, v36
	v_mov_b32_e32 v59, v38
	v_mov_b32_e32 v60, v48
	v_mov_b32_e32 v61, v50
	v_mov_b32_e32 v38, v37
	v_mov_b32_e32 v50, v49
	v_mov_b32_e32 v62, v52
	v_mov_b32_e32 v63, v54
	v_mov_b32_e32 v54, v53
	v_pk_mul_f32 v[36:37], v[40:41], v[58:59]
	v_pk_add_f32 v[40:41], v[60:61], 1.0 op_sel_hi:[1,0]
	v_pk_mul_f32 v[38:39], v[42:43], v[38:39]
	v_pk_add_f32 v[42:43], v[50:51], 1.0 op_sel_hi:[1,0]
	v_pk_fma_f32 v[36:37], v[36:37], v[40:41], v[62:63]
	v_pk_fma_f32 v[38:39], v[38:39], v[42:43], v[54:55]
	v_and_b32_sdwa v19, v36, v177 dst_sel:DWORD dst_unused:UNUSED_PAD src0_sel:WORD_1 src1_sel:DWORD
	v_and_b32_sdwa v23, v39, v177 dst_sel:DWORD dst_unused:UNUSED_PAD src0_sel:WORD_1 src1_sel:DWORD
	v_and_b32_sdwa v40, v38, v177 dst_sel:DWORD dst_unused:UNUSED_PAD src0_sel:WORD_1 src1_sel:DWORD
	v_and_b32_sdwa v7, v37, v177 dst_sel:DWORD dst_unused:UNUSED_PAD src0_sel:WORD_1 src1_sel:DWORD
	v_add3_u32 v19, v36, v19, s28
	v_add3_u32 v23, v39, v23, s28
	v_add3_u32 v36, v38, v40, s28
	v_add3_u32 v7, v37, v7, s28
	v_and_b32_e32 v23, 0xffff0000, v23
	v_and_b32_e32 v36, 0xffff0000, v36
	v_or_b32_sdwa v37, v23, v7 dst_sel:DWORD dst_unused:UNUSED_PAD src0_sel:DWORD src1_sel:WORD_1
	v_or_b32_sdwa v36, v36, v19 dst_sel:DWORD dst_unused:UNUSED_PAD src0_sel:DWORD src1_sel:WORD_1
	global_store_dwordx2 v[24:25], v[36:37], off offset:512
	v_lshl_add_u64 v[40:41], v[26:27], 0, v[20:21]
	v_mov_b32_e32 v48, v98
	v_mov_b32_e32 v49, v99
	v_mov_b32_e32 v50, v100
	v_mov_b32_e32 v51, v101
	v_mov_b32_e32 v40, v94
	v_mov_b32_e32 v41, v95
	v_mov_b32_e32 v42, v96
	v_mov_b32_e32 v43, v97
	v_mov_b32_e32 v36, v90
	v_mov_b32_e32 v37, v91
	v_mov_b32_e32 v38, v92
	v_mov_b32_e32 v39, v93
	v_mov_b32_e32 v52, v44
	v_mov_b32_e32 v53, v46
	v_mov_b32_e32 v44, v45
	v_mov_b32_e32 v45, v47
	v_pk_mul_f32 v[46:47], v[52:53], v[56:57] op_sel_hi:[1,0]
	v_pk_mul_f32 v[44:45], v[44:45], v[56:57] op_sel_hi:[1,0]
	v_mov_b32_e32 v23, v1
	v_lshl_add_u64 v[26:27], v[26:27], 0, v[22:23]
	v_mov_b32_e32 v52, v36
	v_mov_b32_e32 v53, v38
	v_mov_b32_e32 v54, v40
	v_mov_b32_e32 v55, v42
	v_mov_b32_e32 v38, v37
	v_mov_b32_e32 v42, v41
	v_mov_b32_e32 v58, v48
	v_mov_b32_e32 v59, v50
	v_mov_b32_e32 v50, v49
	v_pk_mul_f32 v[36:37], v[46:47], v[52:53]
	v_pk_add_f32 v[40:41], v[54:55], 1.0 op_sel_hi:[1,0]
	v_pk_mul_f32 v[38:39], v[44:45], v[38:39]
	v_pk_add_f32 v[42:43], v[42:43], 1.0 op_sel_hi:[1,0]
	v_pk_fma_f32 v[36:37], v[36:37], v[40:41], v[58:59]
	v_pk_fma_f32 v[38:39], v[38:39], v[42:43], v[50:51]
	v_and_b32_sdwa v19, v36, v177 dst_sel:DWORD dst_unused:UNUSED_PAD src0_sel:WORD_1 src1_sel:DWORD
	v_and_b32_sdwa v21, v39, v177 dst_sel:DWORD dst_unused:UNUSED_PAD src0_sel:WORD_1 src1_sel:DWORD
	v_and_b32_sdwa v40, v38, v177 dst_sel:DWORD dst_unused:UNUSED_PAD src0_sel:WORD_1 src1_sel:DWORD
	v_and_b32_sdwa v7, v37, v177 dst_sel:DWORD dst_unused:UNUSED_PAD src0_sel:WORD_1 src1_sel:DWORD
	v_add3_u32 v19, v36, v19, s28
	v_add3_u32 v21, v39, v21, s28
	v_add3_u32 v36, v38, v40, s28
	v_add3_u32 v7, v37, v7, s28
	v_and_b32_e32 v21, 0xffff0000, v21
	v_and_b32_e32 v36, 0xffff0000, v36
	v_or_b32_sdwa v37, v21, v7 dst_sel:DWORD dst_unused:UNUSED_PAD src0_sel:DWORD src1_sel:WORD_1
	v_or_b32_sdwa v36, v36, v19 dst_sel:DWORD dst_unused:UNUSED_PAD src0_sel:DWORD src1_sel:WORD_1
	global_store_dwordx2 v[24:25], v[36:37], off offset:1024
	v_mov_b32_e32 v26, v110
	v_mov_b32_e32 v27, v111
	v_mov_b32_e32 v28, v112
	v_mov_b32_e32 v29, v113
	v_mov_b32_e32 v40, v106
	v_mov_b32_e32 v41, v107
	v_mov_b32_e32 v42, v108
	v_mov_b32_e32 v43, v109
	v_mov_b32_e32 v36, v102
	v_mov_b32_e32 v37, v103
	v_mov_b32_e32 v38, v104
	v_mov_b32_e32 v39, v105
	v_mov_b32_e32 v44, v2
	v_mov_b32_e32 v45, v4
	v_mov_b32_e32 v4, v3
	v_pk_mul_f32 v[2:3], v[44:45], v[56:57] op_sel_hi:[1,0]
	v_pk_mul_f32 v[4:5], v[4:5], v[56:57] op_sel_hi:[1,0]
	v_mov_b32_e32 v47, v42
	v_mov_b32_e32 v45, v38
	v_mov_b32_e32 v38, v37
	v_mov_b32_e32 v42, v41
	v_mov_b32_e32 v44, v36
	v_mov_b32_e32 v46, v40
	v_mov_b32_e32 v49, v28
	v_mov_b32_e32 v28, v27
	v_pk_mul_f32 v[4:5], v[4:5], v[38:39]
	v_pk_add_f32 v[36:37], v[42:43], 1.0 op_sel_hi:[1,0]
	v_mov_b32_e32 v48, v26
	v_pk_mul_f32 v[2:3], v[2:3], v[44:45]
	v_pk_add_f32 v[26:27], v[46:47], 1.0 op_sel_hi:[1,0]
	v_pk_fma_f32 v[4:5], v[4:5], v[36:37], v[28:29]
	v_pk_fma_f32 v[2:3], v[2:3], v[26:27], v[48:49]
	v_and_b32_sdwa v21, v5, v177 dst_sel:DWORD dst_unused:UNUSED_PAD src0_sel:WORD_1 src1_sel:DWORD
	v_and_b32_sdwa v23, v4, v177 dst_sel:DWORD dst_unused:UNUSED_PAD src0_sel:WORD_1 src1_sel:DWORD
	v_and_b32_sdwa v7, v3, v177 dst_sel:DWORD dst_unused:UNUSED_PAD src0_sel:WORD_1 src1_sel:DWORD
	v_and_b32_sdwa v19, v2, v177 dst_sel:DWORD dst_unused:UNUSED_PAD src0_sel:WORD_1 src1_sel:DWORD
	v_add3_u32 v5, v5, v21, s28
	v_add3_u32 v4, v4, v23, s28
	v_add3_u32 v2, v2, v19, s28
	v_add3_u32 v3, v3, v7, s28
	v_and_b32_e32 v5, 0xffff0000, v5
	v_and_b32_e32 v4, 0xffff0000, v4
	v_or_b32_sdwa v3, v5, v3 dst_sel:DWORD dst_unused:UNUSED_PAD src0_sel:DWORD src1_sel:WORD_1
	v_or_b32_sdwa v2, v4, v2 dst_sel:DWORD dst_unused:UNUSED_PAD src0_sel:DWORD src1_sel:WORD_1
	global_store_dwordx2 v[24:25], v[2:3], off offset:1536
	s_nop 0
	v_lshl_add_u32 v6, s4, 3, v6
	v_cmp_lt_i32_e32 vcc, s29, v6
	s_or_b64 s[18:19], vcc, s[18:19]
	s_andn2_b64 exec, exec, s[18:19]
	s_cbranch_execz .LBB0_609

.LBB0_609:
	s_or_b64 exec, exec, s[12:13]
	s_waitcnt vmcnt(0)
	v_readlane_b32 s2, v253, 0
	v_readlane_b32 s3, v253, 1
	s_barrier
	s_and_saveexec_b64 s[6:7], s[2:3]
	s_xor_b64 s[12:13], exec, s[6:7]
	s_cbranch_execz .LBB0_662
	s_waitcnt vmcnt(0) expcnt(0) lgkmcnt(0)
	ds_read_b32 v3, v175
	ds_read_b32 v2, v176
	s_waitcnt lgkmcnt(0)
	v_cmp_ne_u32_e32 vcc, 0, v3
	s_cbranch_vccnz .LBB0_625
	s_mov_b32 s4, 1
	s_branch .LBB0_613

.LBB0_1379:
	s_or_b64 exec, exec, s[46:47]
	v_lshl_add_u64 v[2:3], v[2:3], 0, v[0:1]
	global_load_dwordx4 v[36:39], v[2:3], off
	global_load_dwordx4 v[40:43], v[2:3], off offset:1024
	global_load_dwordx4 v[44:47], v[2:3], off offset:2048
	s_nop 0
	global_load_dwordx4 v[2:5], v[2:3], off offset:3072
	s_nop 0
	global_load_dwordx4 v[48:51], v[8:9], off
	global_load_dwordx4 v[78:81], v[10:11], off
	global_load_dwordx4 v[90:93], v[12:13], off
	global_load_dwordx4 v[102:105], v[14:15], off
	v_min_i32_e32 v19, 0x4000, v6
	v_ashrrev_i32_e32 v19, 11, v19
	v_mul_hi_i32_i24_e32 v25, 0x9000, v19
	v_mul_i32_i24_e32 v24, 0x9000, v19
	v_lshl_add_u64 v[24:25], s[16:17], 0, v[24:25]
	v_lshl_add_u64 v[26:27], v[24:25], 0, s[38:39]
	v_lshl_add_u64 v[28:29], v[26:27], 0, v[0:1]
	global_load_dwordx4 v[52:55], v[28:29], off
	global_load_dwordx4 v[82:85], v[28:29], off offset:1024
	global_load_dwordx4 v[94:97], v[28:29], off offset:2048
	global_load_dwordx4 v[106:109], v[28:29], off offset:3072
	v_lshl_add_u64 v[28:29], v[24:25], 0, v[0:1]
	global_load_dwordx4 v[56:59], v[28:29], off
	global_load_dwordx4 v[86:89], v[28:29], off offset:1024
	global_load_dwordx4 v[98:101], v[28:29], off offset:2048
	global_load_dwordx4 v[110:113], v[28:29], off offset:3072
	s_mov_b32 s2, s42
	s_waitcnt vmcnt(15)
	v_mov_b32_e32 v60, v37
	s_waitcnt vmcnt(14)
	v_mov_b32_e32 v61, v41
	v_mov_b32_e32 v24, v36
	v_mov_b32_e32 v25, v40
	s_waitcnt vmcnt(13)
	v_mov_b32_e32 v68, v45
	s_waitcnt vmcnt(12)
	v_mov_b32_e32 v69, v3
	v_pk_mul_f32 v[60:61], v[60:61], v[60:61]
	v_mov_b32_e32 v62, v38
	v_mov_b32_e32 v63, v42
	v_mov_b32_e32 v66, v44
	v_mov_b32_e32 v67, v2
	v_pk_mul_f32 v[68:69], v[68:69], v[68:69]
	v_pk_fma_f32 v[24:25], v[24:25], v[24:25], v[60:61]
	v_mov_b32_e32 v64, v39
	v_mov_b32_e32 v65, v43
	v_mov_b32_e32 v70, v46
	v_mov_b32_e32 v71, v4
	v_pk_fma_f32 v[60:61], v[66:67], v[66:67], v[68:69]
	v_pk_fma_f32 v[24:25], v[62:63], v[62:63], v[24:25]
	v_mov_b32_e32 v72, v47
	v_mov_b32_e32 v73, v5
	v_pk_fma_f32 v[60:61], v[70:71], v[70:71], v[60:61]
	v_pk_fma_f32 v[24:25], v[64:65], v[64:65], v[24:25]
	v_pk_fma_f32 v[60:61], v[72:73], v[72:73], v[60:61]
	v_add_f32_e32 v19, v24, v25
	v_add_f32_e32 v19, v19, v60
	v_add_f32_e32 v19, v19, v61
	ds_bpermute_b32 v21, v30, v19
	v_lshlrev_b64 v[24:25], 11, v[6:7]
	s_waitcnt vmcnt(11)
	v_mov_b32_e32 v60, v48
	v_mov_b32_e32 v48, v36
	v_mov_b32_e32 v36, v37
	s_waitcnt lgkmcnt(0)
	v_add_f32_e32 v19, v19, v21
	ds_bpermute_b32 v21, v31, v19
	v_mov_b32_e32 v37, v39
	s_waitcnt vmcnt(3)
	v_mov_b32_e32 v62, v56
	v_mov_b32_e32 v61, v50
	v_mov_b32_e32 v50, v49
	s_waitcnt lgkmcnt(0)
	v_add_f32_e32 v21, v19, v21
	v_mov_b32_e32 v49, v38
	v_mov_b32_e32 v39, v54
	v_mov_b32_e32 v54, v53
	v_mov_b32_e32 v38, v52
	s_waitcnt lgkmcnt(0)
	s_nop 1
	v_add_f32_dpp v7, v21, v21 row_ror:8 row_mask:0xf bank_mask:0xf bound_ctrl:1
	v_mov_b32_e32 v63, v58
	v_mov_b32_e32 v58, v57
	v_pk_add_f32 v[52:53], v[54:55], 1.0 op_sel_hi:[1,0]
	v_pk_add_f32 v[38:39], v[38:39], 1.0 op_sel_hi:[1,0]
	s_waitcnt lgkmcnt(0)
	s_nop 1
	v_add_f32_dpp v7, v7, v7 row_ror:4 row_mask:0xf bank_mask:0xf bound_ctrl:1
	v_lshl_add_u64 v[24:25], v[16:17], 0, v[24:25]
	v_mov_b32_e32 v19, v1
	s_waitcnt lgkmcnt(0)
	s_nop 1
	v_add_f32_dpp v7, v7, v7 quad_perm:[2,3,0,1] row_mask:0xf bank_mask:0xf bound_ctrl:1
	s_waitcnt lgkmcnt(0)
	s_nop 1
	v_add_f32_dpp v7, v7, v7 quad_perm:[1,0,3,2] row_mask:0xf bank_mask:0xf bound_ctrl:1
	v_fmamk_f32 v7, v7, 0x3a800000, v174
	v_mul_f32_e32 v21, 0x4b800000, v7
	v_cmp_gt_f32_e32 vcc, s27, v7
	s_nop 1
	v_cndmask_b32_e32 v7, v7, v21, vcc
	v_rsq_f32_e32 v7, v7
	s_nop 0
	v_mul_f32_e32 v21, 0x45800000, v7
	v_cndmask_b32_e32 v56, v7, v21, vcc
	v_pk_mul_f32 v[36:37], v[36:37], v[56:57] op_sel_hi:[1,0]
	v_pk_mul_f32 v[48:49], v[48:49], v[56:57] op_sel_hi:[1,0]
	v_pk_mul_f32 v[36:37], v[50:51], v[36:37]
	v_pk_mul_f32 v[48:49], v[60:61], v[48:49]
	v_pk_fma_f32 v[36:37], v[52:53], v[36:37], v[58:59]
	v_pk_fma_f32 v[38:39], v[38:39], v[48:49], v[62:63]
	v_and_b32_sdwa v23, v37, v177 dst_sel:DWORD dst_unused:UNUSED_PAD src0_sel:WORD_1 src1_sel:DWORD
	v_and_b32_sdwa v48, v36, v177 dst_sel:DWORD dst_unused:UNUSED_PAD src0_sel:WORD_1 src1_sel:DWORD
	v_and_b32_sdwa v7, v39, v177 dst_sel:DWORD dst_unused:UNUSED_PAD src0_sel:WORD_1 src1_sel:DWORD
	v_and_b32_sdwa v21, v38, v177 dst_sel:DWORD dst_unused:UNUSED_PAD src0_sel:WORD_1 src1_sel:DWORD
	v_add3_u32 v23, v37, v23, s28
	v_add3_u32 v36, v36, v48, s28
	v_add3_u32 v21, v38, v21, s28
	v_add3_u32 v7, v39, v7, s28
	v_and_b32_e32 v23, 0xffff0000, v23
	v_and_b32_e32 v36, 0xffff0000, v36
	v_or_b32_sdwa v37, v23, v7 dst_sel:DWORD dst_unused:UNUSED_PAD src0_sel:DWORD src1_sel:WORD_1
	v_or_b32_sdwa v36, v36, v21 dst_sel:DWORD dst_unused:UNUSED_PAD src0_sel:DWORD src1_sel:WORD_1
	global_store_dwordx2 v[24:25], v[36:37], off
	v_lshl_add_u64 v[48:49], v[26:27], 0, v[18:19]
	s_waitcnt vmcnt(1)
	v_mov_b32_e32 v52, v86
	v_mov_b32_e32 v53, v87
	v_mov_b32_e32 v54, v88
	v_mov_b32_e32 v55, v89
	v_mov_b32_e32 v48, v82
	v_mov_b32_e32 v49, v83
	v_mov_b32_e32 v50, v84
	v_mov_b32_e32 v51, v85
	v_mov_b32_e32 v36, v78
	v_mov_b32_e32 v37, v79
	v_mov_b32_e32 v38, v80
	v_mov_b32_e32 v39, v81
	v_mov_b32_e32 v58, v40
	v_mov_b32_e32 v59, v42
	v_mov_b32_e32 v42, v41
	v_pk_mul_f32 v[40:41], v[58:59], v[56:57] op_sel_hi:[1,0]
	v_pk_mul_f32 v[42:43], v[42:43], v[56:57] op_sel_hi:[1,0]
	v_mov_b32_e32 v21, v1
	v_mov_b32_e32 v58, v36
	v_mov_b32_e32 v59, v38
	v_mov_b32_e32 v60, v48
	v_mov_b32_e32 v61, v50
	v_mov_b32_e32 v38, v37
	v_mov_b32_e32 v50, v49
	v_mov_b32_e32 v62, v52
	v_mov_b32_e32 v63, v54
	v_mov_b32_e32 v54, v53
	v_pk_mul_f32 v[36:37], v[40:41], v[58:59]
	v_pk_add_f32 v[40:41], v[60:61], 1.0 op_sel_hi:[1,0]
	v_pk_mul_f32 v[38:39], v[42:43], v[38:39]
	v_pk_add_f32 v[42:43], v[50:51], 1.0 op_sel_hi:[1,0]
	v_pk_fma_f32 v[36:37], v[36:37], v[40:41], v[62:63]
	v_pk_fma_f32 v[38:39], v[38:39], v[42:43], v[54:55]
	v_and_b32_sdwa v19, v36, v177 dst_sel:DWORD dst_unused:UNUSED_PAD src0_sel:WORD_1 src1_sel:DWORD
	v_and_b32_sdwa v23, v39, v177 dst_sel:DWORD dst_unused:UNUSED_PAD src0_sel:WORD_1 src1_sel:DWORD
	v_and_b32_sdwa v40, v38, v177 dst_sel:DWORD dst_unused:UNUSED_PAD src0_sel:WORD_1 src1_sel:DWORD
	v_and_b32_sdwa v7, v37, v177 dst_sel:DWORD dst_unused:UNUSED_PAD src0_sel:WORD_1 src1_sel:DWORD
	v_add3_u32 v19, v36, v19, s28
	v_add3_u32 v23, v39, v23, s28
	v_add3_u32 v36, v38, v40, s28
	v_add3_u32 v7, v37, v7, s28
	v_and_b32_e32 v23, 0xffff0000, v23
	v_and_b32_e32 v36, 0xffff0000, v36
	v_or_b32_sdwa v37, v23, v7 dst_sel:DWORD dst_unused:UNUSED_PAD src0_sel:DWORD src1_sel:WORD_1
	v_or_b32_sdwa v36, v36, v19 dst_sel:DWORD dst_unused:UNUSED_PAD src0_sel:DWORD src1_sel:WORD_1
	global_store_dwordx2 v[24:25], v[36:37], off offset:512
	v_lshl_add_u64 v[40:41], v[26:27], 0, v[20:21]
	v_mov_b32_e32 v48, v98
	v_mov_b32_e32 v49, v99
	v_mov_b32_e32 v50, v100
	v_mov_b32_e32 v51, v101
	v_mov_b32_e32 v40, v94
	v_mov_b32_e32 v41, v95
	v_mov_b32_e32 v42, v96
	v_mov_b32_e32 v43, v97
	v_mov_b32_e32 v36, v90
	v_mov_b32_e32 v37, v91
	v_mov_b32_e32 v38, v92
	v_mov_b32_e32 v39, v93
	v_mov_b32_e32 v52, v44
	v_mov_b32_e32 v53, v46
	v_mov_b32_e32 v44, v45
	v_mov_b32_e32 v45, v47
	v_pk_mul_f32 v[46:47], v[52:53], v[56:57] op_sel_hi:[1,0]
	v_pk_mul_f32 v[44:45], v[44:45], v[56:57] op_sel_hi:[1,0]
	v_mov_b32_e32 v23, v1
	v_lshl_add_u64 v[26:27], v[26:27], 0, v[22:23]
	v_mov_b32_e32 v52, v36
	v_mov_b32_e32 v53, v38
	v_mov_b32_e32 v54, v40
	v_mov_b32_e32 v55, v42
	v_mov_b32_e32 v38, v37
	v_mov_b32_e32 v42, v41
	v_mov_b32_e32 v58, v48
	v_mov_b32_e32 v59, v50
	v_mov_b32_e32 v50, v49
	v_pk_mul_f32 v[36:37], v[46:47], v[52:53]
	v_pk_add_f32 v[40:41], v[54:55], 1.0 op_sel_hi:[1,0]
	v_pk_mul_f32 v[38:39], v[44:45], v[38:39]
	v_pk_add_f32 v[42:43], v[42:43], 1.0 op_sel_hi:[1,0]
	v_pk_fma_f32 v[36:37], v[36:37], v[40:41], v[58:59]
	v_pk_fma_f32 v[38:39], v[38:39], v[42:43], v[50:51]
	v_and_b32_sdwa v19, v36, v177 dst_sel:DWORD dst_unused:UNUSED_PAD src0_sel:WORD_1 src1_sel:DWORD
	v_and_b32_sdwa v21, v39, v177 dst_sel:DWORD dst_unused:UNUSED_PAD src0_sel:WORD_1 src1_sel:DWORD
	v_and_b32_sdwa v40, v38, v177 dst_sel:DWORD dst_unused:UNUSED_PAD src0_sel:WORD_1 src1_sel:DWORD
	v_and_b32_sdwa v7, v37, v177 dst_sel:DWORD dst_unused:UNUSED_PAD src0_sel:WORD_1 src1_sel:DWORD
	v_add3_u32 v19, v36, v19, s28
	v_add3_u32 v21, v39, v21, s28
	v_add3_u32 v36, v38, v40, s28
	v_add3_u32 v7, v37, v7, s28
	v_and_b32_e32 v21, 0xffff0000, v21
	v_and_b32_e32 v36, 0xffff0000, v36
	v_or_b32_sdwa v37, v21, v7 dst_sel:DWORD dst_unused:UNUSED_PAD src0_sel:DWORD src1_sel:WORD_1
	v_or_b32_sdwa v36, v36, v19 dst_sel:DWORD dst_unused:UNUSED_PAD src0_sel:DWORD src1_sel:WORD_1
	global_store_dwordx2 v[24:25], v[36:37], off offset:1024
	v_mov_b32_e32 v26, v110
	v_mov_b32_e32 v27, v111
	v_mov_b32_e32 v28, v112
	v_mov_b32_e32 v29, v113
	v_mov_b32_e32 v40, v106
	v_mov_b32_e32 v41, v107
	v_mov_b32_e32 v42, v108
	v_mov_b32_e32 v43, v109
	v_mov_b32_e32 v36, v102
	v_mov_b32_e32 v37, v103
	v_mov_b32_e32 v38, v104
	v_mov_b32_e32 v39, v105
	v_mov_b32_e32 v44, v2
	v_mov_b32_e32 v45, v4
	v_mov_b32_e32 v4, v3
	v_pk_mul_f32 v[2:3], v[44:45], v[56:57] op_sel_hi:[1,0]
	v_pk_mul_f32 v[4:5], v[4:5], v[56:57] op_sel_hi:[1,0]
	v_mov_b32_e32 v47, v42
	v_mov_b32_e32 v45, v38
	v_mov_b32_e32 v38, v37
	v_mov_b32_e32 v42, v41
	v_mov_b32_e32 v44, v36
	v_mov_b32_e32 v46, v40
	v_mov_b32_e32 v49, v28
	v_mov_b32_e32 v28, v27
	v_pk_mul_f32 v[4:5], v[4:5], v[38:39]
	v_pk_add_f32 v[36:37], v[42:43], 1.0 op_sel_hi:[1,0]
	v_mov_b32_e32 v48, v26
	v_pk_mul_f32 v[2:3], v[2:3], v[44:45]
	v_pk_add_f32 v[26:27], v[46:47], 1.0 op_sel_hi:[1,0]
	v_pk_fma_f32 v[4:5], v[4:5], v[36:37], v[28:29]
	v_pk_fma_f32 v[2:3], v[2:3], v[26:27], v[48:49]
	v_and_b32_sdwa v21, v5, v177 dst_sel:DWORD dst_unused:UNUSED_PAD src0_sel:WORD_1 src1_sel:DWORD
	v_and_b32_sdwa v23, v4, v177 dst_sel:DWORD dst_unused:UNUSED_PAD src0_sel:WORD_1 src1_sel:DWORD
	v_and_b32_sdwa v7, v3, v177 dst_sel:DWORD dst_unused:UNUSED_PAD src0_sel:WORD_1 src1_sel:DWORD
	v_and_b32_sdwa v19, v2, v177 dst_sel:DWORD dst_unused:UNUSED_PAD src0_sel:WORD_1 src1_sel:DWORD
	v_add3_u32 v5, v5, v21, s28
	v_add3_u32 v4, v4, v23, s28
	v_add3_u32 v2, v2, v19, s28
	v_add3_u32 v3, v3, v7, s28
	v_and_b32_e32 v5, 0xffff0000, v5
	v_and_b32_e32 v4, 0xffff0000, v4
	v_or_b32_sdwa v3, v5, v3 dst_sel:DWORD dst_unused:UNUSED_PAD src0_sel:DWORD src1_sel:WORD_1
	v_or_b32_sdwa v2, v4, v2 dst_sel:DWORD dst_unused:UNUSED_PAD src0_sel:DWORD src1_sel:WORD_1
	global_store_dwordx2 v[24:25], v[2:3], off offset:1536
	s_nop 0
	v_lshl_add_u32 v6, s2, 3, v6
	v_cmp_le_i32_e32 vcc, s11, v6
	s_or_b64 s[18:19], vcc, s[18:19]
	s_andn2_b64 exec, exec, s[18:19]
	s_cbranch_execz .LBB0_1384
